# GEMM unit headers: tile-order arithmetic constant-folded per phase (no runtime division sequence between epilogue and next K-loop)
# speedup vs baseline: 1.0015x; 1.0015x over previous
;     __device__ bool next(int i, pg8::Unit& u) const { const int L = i * G + c; if (L >= 1280) return false; u.pn = L >> 6; u.pm = (L & 63) + (u.pn >= 16 ? 64 : 0); return true; }
;     __host__ __device__ bool next(int i, Unit& u) const {
;         const long L = (long)i * G + c; if (L >= nwg) return false;
;         int wgid = (int)L; { const int q = nwg / NXCD, r = nwg % NXCD, xcd = wgid % NXCD, off = wgid / NXCD; wgid = (xcd < r ? xcd * (q + 1) : r * (q + 1) + (xcd - r) * q) + off; }
;         const int nig = WGM * nN, gid = wgid / nig, fm = gid * WGM, gsz = (nM - fm) < WGM ? (nM - fm) : WGM;
;         u.pm = fm + ((wgid % nig) % gsz); u.pn = (wgid % nig) / gsz; return true;
;     }
.LBB0_12:
	s_add_i32 s52, s52, 1
	s_mul_i32 s0, s52, s59
	s_mul_hi_u32 s1, s52, s48
	s_add_i32 s1, s1, s0
	s_mul_i32 s0, s52, s48
	v_readlane_b32 s2, v231, 0
	s_add_u32 s2, s0, s2
	s_addc_u32 s3, s1, s42
	v_cmp_ge_i64_e32 vcc, s[2:3], v[144:145]
	v_cmp_lt_i64_e64 s[4:5], s[2:3], v[144:145]
	s_cbranch_vccnz .LBB0_14
	s_and_b32 s0, s2, 7
	s_lshr_b32 s1, s2, 3
	s_mul_i32 s0, s0, 0x100
	s_add_i32 s0, s0, s1
	s_lshr_b32 s1, s0, 7
	s_and_b32 s0, s0, 0x7f
	s_lshr_b32 s65, s0, 2
	s_and_b32 s0, s0, 3
	s_lshl_b32 s1, s1, 2
	s_add_i32 s66, s0, s1

;     __device__ bool next(int i, pg8::Unit& u) const { const int L = i * G + c; if (L >= 1280) return false; u.pn = L >> 6; u.pm = (L & 63) + (u.pn >= 16 ? 64 : 0); return true; }
;     __host__ __device__ bool next(int i, Unit& u) const {
;         const long L = (long)i * G + c; if (L >= nwg) return false;
;         int wgid = (int)L; { const int q = nwg / NXCD, r = nwg % NXCD, xcd = wgid % NXCD, off = wgid / NXCD; wgid = (xcd < r ? xcd * (q + 1) : r * (q + 1) + (xcd - r) * q) + off; }
;         const int nig = WGM * nN, gid = wgid / nig, fm = gid * WGM, gsz = (nM - fm) < WGM ? (nM - fm) : WGM;
;         u.pm = fm + ((wgid % nig) % gsz); u.pn = (wgid % nig) / gsz; return true;
;     }
.LBB0_1092:
	s_add_i32 s67, s67, 1
	s_mul_i32 s0, s67, s74
	s_mul_hi_u32 s1, s67, s52
	s_add_i32 s1, s1, s0
	s_mul_i32 s0, s67, s52
	v_readlane_b32 s2, v231, 0
	s_add_u32 s2, s0, s2
	s_addc_u32 s3, s1, s57
	v_cmp_ge_i64_e32 vcc, s[2:3], v[156:157]
	v_cmp_lt_i64_e64 s[4:5], s[2:3], v[156:157]
	s_cbranch_vccnz .LBB0_1094
	s_and_b32 s0, s2, 7
	s_lshr_b32 s1, s2, 3
	s_mul_i32 s0, s0, 0x80
	s_add_i32 s0, s0, s1
	s_lshr_b32 s1, s0, 6
	s_and_b32 s0, s0, 0x3f
	s_lshr_b32 s86, s0, 2
	s_and_b32 s0, s0, 3
	s_lshl_b32 s1, s1, 2
	s_add_i32 s87, s0, s1

;     __device__ bool next(int i, pg8::Unit& u) const { const int L = i * G + c; if (L >= 1280) return false; u.pn = L >> 6; u.pm = (L & 63) + (u.pn >= 16 ? 64 : 0); return true; }
;     __host__ __device__ bool next(int i, Unit& u) const {
;         const long L = (long)i * G + c; if (L >= nwg) return false;
;         int wgid = (int)L; { const int q = nwg / NXCD, r = nwg % NXCD, xcd = wgid % NXCD, off = wgid / NXCD; wgid = (xcd < r ? xcd * (q + 1) : r * (q + 1) + (xcd - r) * q) + off; }
;         const int nig = WGM * nN, gid = wgid / nig, fm = gid * WGM, gsz = (nM - fm) < WGM ? (nM - fm) : WGM;
;         u.pm = fm + ((wgid % nig) % gsz); u.pn = (wgid % nig) / gsz; return true;
;     }
.LBB0_1171:
	s_add_i32 s46, s46, 1
	s_mul_i32 s0, s46, s54
	s_mul_hi_u32 s1, s46, s48
	s_add_i32 s1, s1, s0
	s_mul_i32 s0, s46, s48
	v_readlane_b32 s2, v231, 0
	s_add_u32 s2, s0, s2
	s_addc_u32 s3, s1, s36
	v_cmp_ge_i64_e32 vcc, s[2:3], v[140:141]
	v_cmp_lt_i64_e64 s[4:5], s[2:3], v[140:141]
	s_cbranch_vccnz .LBB0_1173
	s_and_b32 s0, s2, 7
	s_lshr_b32 s1, s2, 3
	s_mul_i32 s0, s0, 0x40
	s_add_i32 s0, s0, s1
	s_lshr_b32 s1, s0, 5
	s_and_b32 s0, s0, 0x1f
	s_lshr_b32 s57, s0, 2
	s_and_b32 s0, s0, 3
	s_lshl_b32 s1, s1, 2
	s_add_i32 s58, s0, s1

;     __device__ bool next(int i, pg8::Unit& u) const { const int L = i * G + c; if (L >= 1280) return false; u.pn = L >> 6; u.pm = (L & 63) + (u.pn >= 16 ? 64 : 0); return true; }
;     __host__ __device__ bool next(int i, Unit& u) const {
;         const long L = (long)i * G + c; if (L >= nwg) return false;
;         int wgid = (int)L; { const int q = nwg / NXCD, r = nwg % NXCD, xcd = wgid % NXCD, off = wgid / NXCD; wgid = (xcd < r ? xcd * (q + 1) : r * (q + 1) + (xcd - r) * q) + off; }
;         const int nig = WGM * nN, gid = wgid / nig, fm = gid * WGM, gsz = (nM - fm) < WGM ? (nM - fm) : WGM;
;         u.pm = fm + ((wgid % nig) % gsz); u.pn = (wgid % nig) / gsz; return true;
;     }
.LBB0_1250:
	s_add_i32 s51, s51, 1
	s_mul_i32 s0, s51, s58
	s_mul_hi_u32 s1, s51, s48
	s_add_i32 s1, s1, s0
	s_mul_i32 s0, s51, s48
	v_readlane_b32 s2, v231, 0
	s_add_u32 s2, s0, s2
	s_addc_u32 s3, s1, s40
	v_cmp_ge_i64_e32 vcc, s[2:3], v[140:141]
	v_cmp_lt_i64_e64 s[4:5], s[2:3], v[140:141]
	s_cbranch_vccnz .LBB0_1252
	s_and_b32 s0, s2, 7
	s_lshr_b32 s1, s2, 3
	s_mul_i32 s0, s0, 0x40
	s_add_i32 s0, s0, s1
	s_lshr_b32 s1, s0, 5
	s_and_b32 s0, s0, 0x1f
	s_lshr_b32 s62, s0, 2
	s_and_b32 s0, s0, 3
	s_lshl_b32 s1, s1, 2
	s_add_i32 s63, s0, s1

;     __device__ bool next(int i, pg8::Unit& u) const { const int L = i * G + c; if (L >= 1280) return false; u.pn = L >> 6; u.pm = (L & 63) + (u.pn >= 16 ? 64 : 0); return true; }
;     __host__ __device__ bool next(int i, Unit& u) const {
;         const long L = (long)i * G + c; if (L >= nwg) return false;
;         int wgid = (int)L; { const int q = nwg / NXCD, r = nwg % NXCD, xcd = wgid % NXCD, off = wgid / NXCD; wgid = (xcd < r ? xcd * (q + 1) : r * (q + 1) + (xcd - r) * q) + off; }
;         const int nig = WGM * nN, gid = wgid / nig, fm = gid * WGM, gsz = (nM - fm) < WGM ? (nM - fm) : WGM;
;         u.pm = fm + ((wgid % nig) % gsz); u.pn = (wgid % nig) / gsz; return true;
;     }
.LBB0_1331:
	s_add_i32 s64, s64, 1
	s_mul_i32 s0, s64, s57
	s_mul_hi_u32 s1, s64, s48
	s_add_i32 s1, s1, s0
	s_mul_i32 s0, s64, s48
	v_readlane_b32 s2, v231, 0
	s_add_u32 s2, s0, s2
	s_addc_u32 s3, s1, s58
	v_cmp_ge_i64_e32 vcc, s[2:3], v[140:141]
	v_cmp_lt_i64_e64 s[4:5], s[2:3], v[140:141]
	s_cbranch_vccnz .LBB0_1333
	s_and_b32 s0, s2, 7
	s_lshr_b32 s1, s2, 3
	s_mul_i32 s0, s0, 0x40
	s_add_i32 s0, s0, s1
	s_lshr_b32 s1, s0, 5
	s_and_b32 s0, s0, 0x1f
	s_lshr_b32 s65, s0, 2
	s_and_b32 s0, s0, 3
	s_lshl_b32 s1, s1, 2
	s_add_i32 s66, s0, s1

;     __device__ bool next(int i, pg8::Unit& u) const { const int L = i * G + c; if (L >= 1280) return false; u.pn = L >> 6; u.pm = (L & 63) + (u.pn >= 16 ? 64 : 0); return true; }
;     __host__ __device__ bool next(int i, Unit& u) const {
;         const long L = (long)i * G + c; if (L >= nwg) return false;
;         int wgid = (int)L; { const int q = nwg / NXCD, r = nwg % NXCD, xcd = wgid % NXCD, off = wgid / NXCD; wgid = (xcd < r ? xcd * (q + 1) : r * (q + 1) + (xcd - r) * q) + off; }
;         const int nig = WGM * nN, gid = wgid / nig, fm = gid * WGM, gsz = (nM - fm) < WGM ? (nM - fm) : WGM;
;         u.pm = fm + ((wgid % nig) % gsz); u.pn = (wgid % nig) / gsz; return true;
;     }
.LBB0_1487:
	s_add_i32 s49, s49, 1
	s_mul_i32 s0, s49, s56
	s_mul_hi_u32 s1, s49, s48
	s_add_i32 s1, s1, s0
	s_mul_i32 s0, s49, s48
	v_readlane_b32 s2, v231, 0
	s_add_u32 s2, s0, s2
	s_addc_u32 s3, s1, s38
	v_cmp_ge_i64_e32 vcc, s[2:3], v[140:141]
	v_cmp_lt_i64_e64 s[4:5], s[2:3], v[140:141]
	s_cbranch_vccnz .LBB0_1489
	s_and_b32 s0, s2, 7
	s_lshr_b32 s1, s2, 3
	s_mul_i32 s0, s0, 0x160
	s_add_i32 s0, s0, s1
	s_mul_i32 s1, s0, 0xba2f
	s_lshr_b32 s1, s1, 23
	s_mul_i32 s3, s1, 0xb0
	s_sub_i32 s0, s0, s3
	s_lshr_b32 s60, s0, 2
	s_and_b32 s0, s0, 3
	s_lshl_b32 s1, s1, 2
	s_add_i32 s61, s0, s1

;     __device__ bool next(int i, pg8::Unit& u) const { const int L = i * G + c; if (L >= 1280) return false; u.pn = L >> 6; u.pm = (L & 63) + (u.pn >= 16 ? 64 : 0); return true; }
;     __host__ __device__ bool next(int i, Unit& u) const {
;         const long L = (long)i * G + c; if (L >= nwg) return false;
;         int wgid = (int)L; { const int q = nwg / NXCD, r = nwg % NXCD, xcd = wgid % NXCD, off = wgid / NXCD; wgid = (xcd < r ? xcd * (q + 1) : r * (q + 1) + (xcd - r) * q) + off; }
;         const int nig = WGM * nN, gid = wgid / nig, fm = gid * WGM, gsz = (nM - fm) < WGM ? (nM - fm) : WGM;
;         u.pm = fm + ((wgid % nig) % gsz); u.pn = (wgid % nig) / gsz; return true;
;     }
.LBB0_1566:
	s_add_i32 s59, s59, 1
	s_mul_i32 s0, s59, s66
	s_mul_hi_u32 s1, s59, s46
	s_add_i32 s1, s1, s0
	s_mul_i32 s0, s59, s46
	v_readlane_b32 s2, v231, 0
	s_add_u32 s0, s0, s2
	s_addc_u32 s1, s1, s49
	v_cmp_ge_i64_e32 vcc, s[0:1], v[136:137]
	v_cmp_lt_i64_e64 s[2:3], s[0:1], v[136:137]
	s_cbranch_vccnz .LBB0_1568
	s_and_b32 s1, s0, 7
	s_lshr_b32 s33, s0, 3
	s_mul_i32 s1, s1, 0x40
	s_add_i32 s1, s1, s33
	s_lshr_b32 s33, s1, 5
	s_and_b32 s1, s1, 0x1f
	s_lshr_b32 s69, s1, 2
	s_and_b32 s1, s1, 3
	s_lshl_b32 s33, s33, 2
	s_add_i32 s70, s1, s33
